# LDS-DMA staging rebalanced 4+4 per sub-phase in all four large GEMM K-loops (FF1, out-proj/FF2, input projection, final FF2)
# speedup vs baseline: 1.0088x; 1.0031x over previous
.LBB0_259:
	v_mov_b32_e32 v131, v1
	s_cmpk_lt_u32 s5, 0x100
	v_lshl_add_u64 v[14:15], s[40:41], 0, v[0:1]
	v_lshl_add_u64 v[16:17], s[40:41], 0, v[130:131]
	s_cselect_b64 s[40:41], -1, 0
	v_bfe_u32 v200, v8, 4, 2
	s_lshr_b32 s5, s43, 26
	v_and_b32_e32 v199, 15, v8
	s_add_i32 s5, s42, s5
	v_lshlrev_b32_e32 v9, 4, v200
	v_lshlrev_b32_e32 v8, 2, v8
	s_and_b32 s73, s29, 3
	s_ashr_i32 s74, s5, 6
	v_lshl_or_b32 v9, v199, 6, v9
	s_lshl_b32 s5, s28, 13
	v_and_b32_e32 v8, 32, v8
	v_lshl_add_u64 v[10:11], s[58:59], 0, v[0:1]
	v_bitop3_b32 v22, v9, s5, v8 bitop3:0xde
	s_lshl_b32 s5, s73, 12
	v_lshl_add_u64 v[12:13], s[58:59], 0, v[130:131]
	v_mov_b32_e32 v135, v1
	v_bitop3_b32 v201, v9, s5, v8 bitop3:0xde
	s_add_i32 m0, s30, 0x18000
	v_lshl_add_u64 v[8:9], v[10:11], 0, s[24:25]
	v_lshl_add_u64 v[18:19], s[56:57], 0, v[134:135]
	v_mov_b32_e32 v133, v1
	s_waitcnt vmcnt(2)
	s_barrier
	global_load_lds_dwordx4 v[8:9], off
	v_lshl_add_u64 v[8:9], v[12:13], 0, s[24:25]
	s_add_i32 m0, s30, 0x1a000
	s_add_i32 s83, s30, 0x8000
	v_lshl_add_u64 v[20:21], s[56:57], 0, v[132:133]
	global_load_lds_dwordx4 v[8:9], off
	s_add_i32 s38, s30, 0xa000
	s_lshl_b32 s75, s28, 6
	s_add_i32 m0, s30, 0x1c000
	v_lshl_add_u64 v[8:9], v[14:15], 0, s[24:25]
	global_load_lds_dwordx4 v[8:9], off
	v_lshl_add_u64 v[8:9], v[16:17], 0, s[24:25]
	s_add_i32 m0, s30, 0x1e000
	s_lshl_b32 s82, s73, 5
	global_load_lds_dwordx4 v[8:9], off
	s_waitcnt vmcnt(4)
	v_add_u32_e32 v5, v7, v5
	v_add_u32_e32 v2, v4, v2
	s_cmp_gt_i32 s42, 63
	v_add_lshl_u32 v6, v5, v6, 1
	v_mov_b32_e32 v7, v1
	v_add_lshl_u32 v2, v2, v3, 1
	v_mov_b32_e32 v3, v1
	v_readlane_b32 s28, v236, 24
	s_cselect_b64 s[42:43], -1, 0
	s_add_i32 s39, s74, -2
	v_lshl_add_u64 v[136:137], s[2:3], 0, v[6:7]
	v_lshl_add_u64 v[138:139], s[2:3], 0, v[2:3]
	s_mov_b32 s90, 0
	v_add_u32_e32 v202, 0, v22
	v_readlane_b32 s29, v236, 25
	s_mov_b64 s[44:45], s[58:59]
	s_barrier
	s_branch .LBB0_262

.LBB0_266:
	s_add_i32 s60, s58, 2
	s_add_u32 s61, s56, 0x80
	s_addc_u32 s59, s57, 0
	s_add_i32 s64, 0, 0x10000
	s_cmp_eq_u32 s39, s58
	s_cselect_b32 s59, s29, s59
	s_cselect_b32 s58, s50, s61
	s_cselect_b32 s63, s45, s55
	s_cselect_b32 s62, s44, s51
	s_add_i32 s61, 0, 0x14000
	v_add_u32_e32 v152, s64, v201
	v_add_u32_e32 v168, s61, v201
	ds_read_b128 v[140:143], v152
	ds_read_b128 v[144:147], v152 offset:1024
	ds_read_b128 v[148:151], v152 offset:2048
	ds_read_b128 v[152:155], v152 offset:3072
	ds_read_b128 v[156:159], v168
	ds_read_b128 v[160:163], v168 offset:1024
	ds_read_b128 v[164:167], v168 offset:2048
	ds_read_b128 v[168:171], v168 offset:3072
	v_lshl_add_u64 v[188:189], s[56:57], 0, v[134:135]
	s_mov_b32 m0, s83
	ds_read_b128 v[172:175], v202
	ds_read_b128 v[176:179], v202 offset:1024
	ds_read_b128 v[180:183], v202 offset:2048
	ds_read_b128 v[184:187], v202 offset:3072
	ds_read_b128 v[204:207], v202 offset:4096
	ds_read_b128 v[208:211], v202 offset:5120
	ds_read_b128 v[212:215], v202 offset:6144
	ds_read_b128 v[216:219], v202 offset:7168
	global_load_lds_dwordx4 v[188:189], off
	v_lshl_add_u64 v[188:189], s[56:57], 0, v[132:133]
	s_mov_b32 m0, s38
	s_nop 0
	global_load_lds_dwordx4 v[188:189], off
	v_lshl_add_u64 v[188:189], s[56:57], 0, v[136:137]
	s_add_i32 m0, s30, 0xc000
	s_nop 0
	global_load_lds_dwordx4 v[188:189], off
	v_lshl_add_u64 v[188:189], s[56:57], 0, v[138:139]
	s_add_i32 m0, s30, 0xe000
	s_nop 0
	global_load_lds_dwordx4 v[188:189], off
	s_waitcnt vmcnt(8)
	s_waitcnt lgkmcnt(0)
	s_barrier
	s_setprio 1
	s_waitcnt lgkmcnt(0)
	v_mfma_f32_16x16x32_bf16 v[122:125], v[140:143], v[172:175], v[122:125]
	v_mfma_f32_16x16x32_bf16 v[126:129], v[148:151], v[172:175], v[126:129]
	v_mfma_f32_16x16x32_bf16 v[110:113], v[140:143], v[180:183], v[110:113]
	v_mfma_f32_16x16x32_bf16 v[106:109], v[148:151], v[180:183], v[106:109]
	v_mfma_f32_16x16x32_bf16 v[94:97], v[140:143], v[204:207], v[94:97]
	v_mfma_f32_16x16x32_bf16 v[90:93], v[148:151], v[204:207], v[90:93]
	v_mfma_f32_16x16x32_bf16 v[78:81], v[140:143], v[212:215], v[78:81]
	v_mfma_f32_16x16x32_bf16 v[74:77], v[148:151], v[212:215], v[74:77]
	v_mfma_f32_16x16x32_bf16 v[122:125], v[144:147], v[176:179], v[122:125]
	v_mfma_f32_16x16x32_bf16 v[126:129], v[152:155], v[176:179], v[126:129]
	v_mfma_f32_16x16x32_bf16 v[110:113], v[144:147], v[184:187], v[110:113]
	v_mfma_f32_16x16x32_bf16 v[106:109], v[152:155], v[184:187], v[106:109]
	v_mfma_f32_16x16x32_bf16 v[94:97], v[144:147], v[208:211], v[94:97]
	v_mfma_f32_16x16x32_bf16 v[90:93], v[152:155], v[208:211], v[90:93]
	v_mfma_f32_16x16x32_bf16 v[78:81], v[144:147], v[216:219], v[78:81]
	v_mfma_f32_16x16x32_bf16 v[74:77], v[152:155], v[216:219], v[74:77]
	s_setprio 0
	s_setprio 1
	v_mfma_f32_16x16x32_bf16 v[118:121], v[156:159], v[172:175], v[118:121]
	v_mfma_f32_16x16x32_bf16 v[114:117], v[164:167], v[172:175], v[114:117]
	v_mfma_f32_16x16x32_bf16 v[102:105], v[156:159], v[180:183], v[102:105]
	v_mfma_f32_16x16x32_bf16 v[98:101], v[164:167], v[180:183], v[98:101]
	v_mfma_f32_16x16x32_bf16 v[86:89], v[156:159], v[204:207], v[86:89]
	v_mfma_f32_16x16x32_bf16 v[82:85], v[164:167], v[204:207], v[82:85]
	v_mfma_f32_16x16x32_bf16 v[70:73], v[156:159], v[212:215], v[70:73]
	v_mfma_f32_16x16x32_bf16 v[66:69], v[164:167], v[212:215], v[66:69]
	v_mfma_f32_16x16x32_bf16 v[118:121], v[160:163], v[176:179], v[118:121]
	v_mfma_f32_16x16x32_bf16 v[114:117], v[168:171], v[176:179], v[114:117]
	v_mfma_f32_16x16x32_bf16 v[102:105], v[160:163], v[184:187], v[102:105]
	v_mfma_f32_16x16x32_bf16 v[98:101], v[168:171], v[184:187], v[98:101]
	v_mfma_f32_16x16x32_bf16 v[86:89], v[160:163], v[208:211], v[86:89]
	v_mfma_f32_16x16x32_bf16 v[82:85], v[168:171], v[208:211], v[82:85]
	v_mfma_f32_16x16x32_bf16 v[70:73], v[160:163], v[216:219], v[70:73]
	v_mfma_f32_16x16x32_bf16 v[66:69], v[168:171], v[216:219], v[66:69]
	s_setprio 0
	s_barrier
	s_add_i32 s64, s64, s27
	v_lshl_add_u64 v[188:189], s[62:63], 0, v[0:1]
	s_mov_b32 m0, s64
	ds_read_b128 v[172:175], v202 offset:16384
	ds_read_b128 v[176:179], v202 offset:17408
	ds_read_b128 v[180:183], v202 offset:18432
	ds_read_b128 v[184:187], v202 offset:19456
	ds_read_b128 v[204:207], v202 offset:20480
	ds_read_b128 v[208:211], v202 offset:21504
	ds_read_b128 v[212:215], v202 offset:22528
	ds_read_b128 v[216:219], v202 offset:23552
	global_load_lds_dwordx4 v[188:189], off
	s_add_i32 m0, s64, 0x2000
	v_lshl_add_u64 v[220:221], s[62:63], 0, v[130:131]
	s_add_u32 s62, s62, s6
	s_addc_u32 s63, s63, s7
	s_add_i32 s61, s61, s27
	global_load_lds_dwordx4 v[220:221], off
	v_lshl_add_u64 v[222:223], s[62:63], 0, v[0:1]
	s_mov_b32 m0, s61
	v_lshl_add_u64 v[224:225], s[62:63], 0, v[130:131]
	global_load_lds_dwordx4 v[222:223], off
	s_add_i32 m0, s61, 0x2000
	v_lshl_add_u64 v[226:227], s[58:59], 0, v[134:135]
	global_load_lds_dwordx4 v[224:225], off
	v_lshl_add_u64 v[228:229], s[58:59], 0, v[132:133]
	s_waitcnt vmcnt(6)
	s_waitcnt lgkmcnt(0)
	s_barrier
	s_setprio 1
	s_waitcnt lgkmcnt(0)
	v_mfma_f32_16x16x32_bf16 v[62:65], v[140:143], v[172:175], v[62:65]
	v_mfma_f32_16x16x32_bf16 v[58:61], v[148:151], v[172:175], v[58:61]
	v_mfma_f32_16x16x32_bf16 v[46:49], v[140:143], v[180:183], v[46:49]
	v_mfma_f32_16x16x32_bf16 v[42:45], v[148:151], v[180:183], v[42:45]
	v_mfma_f32_16x16x32_bf16 v[30:33], v[140:143], v[204:207], v[30:33]
	v_mfma_f32_16x16x32_bf16 v[26:29], v[148:151], v[204:207], v[26:29]
	v_mfma_f32_16x16x32_bf16 v[14:17], v[140:143], v[212:215], v[14:17]
	v_mfma_f32_16x16x32_bf16 v[10:13], v[148:151], v[212:215], v[10:13]
	v_mfma_f32_16x16x32_bf16 v[62:65], v[144:147], v[176:179], v[62:65]
	v_mfma_f32_16x16x32_bf16 v[58:61], v[152:155], v[176:179], v[58:61]
	v_mfma_f32_16x16x32_bf16 v[46:49], v[144:147], v[184:187], v[46:49]
	v_mfma_f32_16x16x32_bf16 v[42:45], v[152:155], v[184:187], v[42:45]
	v_mfma_f32_16x16x32_bf16 v[30:33], v[144:147], v[208:211], v[30:33]
	v_mfma_f32_16x16x32_bf16 v[26:29], v[152:155], v[208:211], v[26:29]
	v_mfma_f32_16x16x32_bf16 v[14:17], v[144:147], v[216:219], v[14:17]
	v_mfma_f32_16x16x32_bf16 v[10:13], v[152:155], v[216:219], v[10:13]
	s_setprio 0
	s_setprio 1
	v_mfma_f32_16x16x32_bf16 v[54:57], v[156:159], v[172:175], v[54:57]
	v_mfma_f32_16x16x32_bf16 v[50:53], v[164:167], v[172:175], v[50:53]
	v_mfma_f32_16x16x32_bf16 v[38:41], v[156:159], v[180:183], v[38:41]
	v_mfma_f32_16x16x32_bf16 v[34:37], v[164:167], v[180:183], v[34:37]
	v_mfma_f32_16x16x32_bf16 v[22:25], v[156:159], v[204:207], v[22:25]
	v_mfma_f32_16x16x32_bf16 v[18:21], v[164:167], v[204:207], v[18:21]
	v_mfma_f32_16x16x32_bf16 v[6:9], v[156:159], v[212:215], v[6:9]
	v_mfma_f32_16x16x32_bf16 v[2:5], v[164:167], v[212:215], v[2:5]
	v_mfma_f32_16x16x32_bf16 v[54:57], v[160:163], v[176:179], v[54:57]
	v_mfma_f32_16x16x32_bf16 v[50:53], v[168:171], v[176:179], v[50:53]
	v_mfma_f32_16x16x32_bf16 v[38:41], v[160:163], v[184:187], v[38:41]
	v_mfma_f32_16x16x32_bf16 v[34:37], v[168:171], v[184:187], v[34:37]
	v_mfma_f32_16x16x32_bf16 v[22:25], v[160:163], v[208:211], v[22:25]
	v_mfma_f32_16x16x32_bf16 v[18:21], v[168:171], v[208:211], v[18:21]
	v_mfma_f32_16x16x32_bf16 v[6:9], v[160:163], v[216:219], v[6:9]
	v_mfma_f32_16x16x32_bf16 v[2:5], v[168:171], v[216:219], v[2:5]
	s_setprio 0
	s_barrier
	s_add_i32 s61, 0, 0x18000
	s_add_i32 s62, 0, 0x1c000
	v_add_u32_e32 v152, s61, v201
	v_add_u32_e32 v168, s62, v201
	ds_read_b128 v[140:143], v152
	ds_read_b128 v[144:147], v152 offset:1024
	ds_read_b128 v[148:151], v152 offset:2048
	ds_read_b128 v[152:155], v152 offset:3072
	ds_read_b128 v[156:159], v168
	ds_read_b128 v[160:163], v168 offset:1024
	ds_read_b128 v[164:167], v168 offset:2048
	ds_read_b128 v[168:171], v168 offset:3072
	s_add_u32 s58, s58, s2
	s_addc_u32 s59, s59, s3
	s_mov_b32 m0, s30
	v_lshl_add_u64 v[230:231], s[58:59], 0, v[134:135]
	ds_read_b128 v[172:175], v202 offset:32768
	ds_read_b128 v[176:179], v202 offset:33792
	ds_read_b128 v[180:183], v202 offset:34816
	ds_read_b128 v[184:187], v202 offset:35840
	ds_read_b128 v[204:207], v202 offset:36864
	ds_read_b128 v[208:211], v202 offset:37888
	ds_read_b128 v[212:215], v202 offset:38912
	ds_read_b128 v[216:219], v202 offset:39936
	global_load_lds_dwordx4 v[226:227], off
	s_mov_b32 m0, s31
	s_nop 0
	global_load_lds_dwordx4 v[228:229], off
	s_mov_b32 m0, s53
	s_nop 0
	global_load_lds_dwordx4 v[230:231], off
	v_lshl_add_u64 v[230:231], s[58:59], 0, v[132:133]
	s_mov_b32 m0, s72
	s_nop 0
	global_load_lds_dwordx4 v[230:231], off
	s_waitcnt vmcnt(8)
	s_waitcnt lgkmcnt(0)
	s_barrier
	s_setprio 1
	s_waitcnt lgkmcnt(0)
	v_mfma_f32_16x16x32_bf16 v[122:125], v[140:143], v[172:175], v[122:125]
	v_mfma_f32_16x16x32_bf16 v[126:129], v[148:151], v[172:175], v[126:129]
	v_mfma_f32_16x16x32_bf16 v[110:113], v[140:143], v[180:183], v[110:113]
	v_mfma_f32_16x16x32_bf16 v[106:109], v[148:151], v[180:183], v[106:109]
	v_mfma_f32_16x16x32_bf16 v[94:97], v[140:143], v[204:207], v[94:97]
	v_mfma_f32_16x16x32_bf16 v[90:93], v[148:151], v[204:207], v[90:93]
	v_mfma_f32_16x16x32_bf16 v[78:81], v[140:143], v[212:215], v[78:81]
	v_mfma_f32_16x16x32_bf16 v[74:77], v[148:151], v[212:215], v[74:77]
	v_mfma_f32_16x16x32_bf16 v[122:125], v[144:147], v[176:179], v[122:125]
	v_mfma_f32_16x16x32_bf16 v[126:129], v[152:155], v[176:179], v[126:129]
	v_mfma_f32_16x16x32_bf16 v[110:113], v[144:147], v[184:187], v[110:113]
	v_mfma_f32_16x16x32_bf16 v[106:109], v[152:155], v[184:187], v[106:109]
	v_mfma_f32_16x16x32_bf16 v[94:97], v[144:147], v[208:211], v[94:97]
	v_mfma_f32_16x16x32_bf16 v[90:93], v[152:155], v[208:211], v[90:93]
	v_mfma_f32_16x16x32_bf16 v[78:81], v[144:147], v[216:219], v[78:81]
	v_mfma_f32_16x16x32_bf16 v[74:77], v[152:155], v[216:219], v[74:77]
	s_setprio 0
	s_setprio 1
	v_mfma_f32_16x16x32_bf16 v[118:121], v[156:159], v[172:175], v[118:121]
	v_mfma_f32_16x16x32_bf16 v[114:117], v[164:167], v[172:175], v[114:117]
	v_mfma_f32_16x16x32_bf16 v[102:105], v[156:159], v[180:183], v[102:105]
	v_mfma_f32_16x16x32_bf16 v[98:101], v[164:167], v[180:183], v[98:101]
	v_mfma_f32_16x16x32_bf16 v[86:89], v[156:159], v[204:207], v[86:89]
	v_mfma_f32_16x16x32_bf16 v[82:85], v[164:167], v[204:207], v[82:85]
	v_mfma_f32_16x16x32_bf16 v[70:73], v[156:159], v[212:215], v[70:73]
	v_mfma_f32_16x16x32_bf16 v[66:69], v[164:167], v[212:215], v[66:69]
	v_mfma_f32_16x16x32_bf16 v[118:121], v[160:163], v[176:179], v[118:121]
	v_mfma_f32_16x16x32_bf16 v[114:117], v[168:171], v[176:179], v[114:117]
	v_mfma_f32_16x16x32_bf16 v[102:105], v[160:163], v[184:187], v[102:105]
	v_mfma_f32_16x16x32_bf16 v[98:101], v[168:171], v[184:187], v[98:101]
	v_mfma_f32_16x16x32_bf16 v[86:89], v[160:163], v[208:211], v[86:89]
	v_mfma_f32_16x16x32_bf16 v[82:85], v[168:171], v[208:211], v[82:85]
	v_mfma_f32_16x16x32_bf16 v[70:73], v[160:163], v[216:219], v[70:73]
	v_mfma_f32_16x16x32_bf16 v[66:69], v[168:171], v[216:219], v[66:69]
	s_setprio 0
	s_barrier
	s_add_i32 s58, s61, s27
	v_lshl_add_u64 v[188:189], v[188:189], 0, s[24:25]
	s_mov_b32 m0, s58
	ds_read_b128 v[172:175], v202 offset:49152
	ds_read_b128 v[176:179], v202 offset:50176
	ds_read_b128 v[180:183], v202 offset:51200
	ds_read_b128 v[184:187], v202 offset:52224
	ds_read_b128 v[204:207], v202 offset:53248
	ds_read_b128 v[208:211], v202 offset:54272
	ds_read_b128 v[212:215], v202 offset:55296
	ds_read_b128 v[216:219], v202 offset:56320
	global_load_lds_dwordx4 v[188:189], off
	v_lshl_add_u64 v[188:189], v[220:221], 0, s[24:25]
	s_add_i32 m0, s58, 0x2000
	s_add_i32 s58, s62, s27
	global_load_lds_dwordx4 v[188:189], off
	v_lshl_add_u64 v[188:189], v[222:223], 0, s[24:25]
	s_mov_b32 m0, s58
	s_nop 0
	global_load_lds_dwordx4 v[188:189], off
	v_lshl_add_u64 v[188:189], v[224:225], 0, s[24:25]
	s_add_i32 m0, s58, 0x2000
	s_nop 0
	global_load_lds_dwordx4 v[188:189], off
	s_waitcnt vmcnt(6)
	s_waitcnt lgkmcnt(0)
	s_barrier
	s_setprio 1
	s_waitcnt lgkmcnt(0)
	v_mfma_f32_16x16x32_bf16 v[62:65], v[140:143], v[172:175], v[62:65]
	v_mfma_f32_16x16x32_bf16 v[58:61], v[148:151], v[172:175], v[58:61]
	v_mfma_f32_16x16x32_bf16 v[46:49], v[140:143], v[180:183], v[46:49]
	v_mfma_f32_16x16x32_bf16 v[42:45], v[148:151], v[180:183], v[42:45]
	v_mfma_f32_16x16x32_bf16 v[30:33], v[140:143], v[204:207], v[30:33]
	v_mfma_f32_16x16x32_bf16 v[26:29], v[148:151], v[204:207], v[26:29]
	v_mfma_f32_16x16x32_bf16 v[14:17], v[140:143], v[212:215], v[14:17]
	v_mfma_f32_16x16x32_bf16 v[10:13], v[148:151], v[212:215], v[10:13]
	v_mfma_f32_16x16x32_bf16 v[62:65], v[144:147], v[176:179], v[62:65]
	v_mfma_f32_16x16x32_bf16 v[58:61], v[152:155], v[176:179], v[58:61]
	v_mfma_f32_16x16x32_bf16 v[46:49], v[144:147], v[184:187], v[46:49]
	v_mfma_f32_16x16x32_bf16 v[42:45], v[152:155], v[184:187], v[42:45]
	v_mfma_f32_16x16x32_bf16 v[30:33], v[144:147], v[208:211], v[30:33]
	v_mfma_f32_16x16x32_bf16 v[26:29], v[152:155], v[208:211], v[26:29]
	v_mfma_f32_16x16x32_bf16 v[14:17], v[144:147], v[216:219], v[14:17]
	v_mfma_f32_16x16x32_bf16 v[10:13], v[152:155], v[216:219], v[10:13]
	s_setprio 0
	s_setprio 1
	v_mfma_f32_16x16x32_bf16 v[54:57], v[156:159], v[172:175], v[54:57]
	v_mfma_f32_16x16x32_bf16 v[50:53], v[164:167], v[172:175], v[50:53]
	v_mfma_f32_16x16x32_bf16 v[38:41], v[156:159], v[180:183], v[38:41]
	v_mfma_f32_16x16x32_bf16 v[34:37], v[164:167], v[180:183], v[34:37]
	v_mfma_f32_16x16x32_bf16 v[22:25], v[156:159], v[204:207], v[22:25]
	v_mfma_f32_16x16x32_bf16 v[18:21], v[164:167], v[204:207], v[18:21]
	v_mfma_f32_16x16x32_bf16 v[6:9], v[156:159], v[212:215], v[6:9]
	v_mfma_f32_16x16x32_bf16 v[2:5], v[164:167], v[212:215], v[2:5]
	v_mfma_f32_16x16x32_bf16 v[54:57], v[160:163], v[176:179], v[54:57]
	v_mfma_f32_16x16x32_bf16 v[50:53], v[168:171], v[176:179], v[50:53]
	v_mfma_f32_16x16x32_bf16 v[38:41], v[160:163], v[184:187], v[38:41]
	v_mfma_f32_16x16x32_bf16 v[34:37], v[168:171], v[184:187], v[34:37]
	v_mfma_f32_16x16x32_bf16 v[22:25], v[160:163], v[208:211], v[22:25]
	v_mfma_f32_16x16x32_bf16 v[18:21], v[168:171], v[208:211], v[18:21]
	v_mfma_f32_16x16x32_bf16 v[6:9], v[160:163], v[216:219], v[6:9]
	v_mfma_f32_16x16x32_bf16 v[2:5], v[168:171], v[216:219], v[2:5]
	s_setprio 0
	s_barrier
	s_add_u32 s56, s56, 0x100
	s_addc_u32 s57, s57, 0
	s_add_u32 s51, s51, 0x100
	s_addc_u32 s55, s55, 0
	s_cmp_ge_i32 s60, s74
	s_mov_b32 s58, s60
	s_cbranch_scc0 .LBB0_266

.LBB0_460:
	v_mov_b32_e32 v151, v1
	v_lshl_add_u64 v[26:27], s[42:43], 0, v[150:151]
	v_mov_b32_e32 v147, v1
	v_lshl_add_u64 v[28:29], s[42:43], 0, v[146:147]
	v_mov_b32_e32 v153, v1
	s_add_i32 m0, s53, 0x18000
	v_lshl_add_u64 v[26:27], v[26:27], 0, s[24:25]
	v_lshl_add_u64 v[34:35], s[40:41], 0, v[152:153]
	v_mov_b32_e32 v149, v1
	s_waitcnt vmcnt(2)
	s_barrier
	global_load_lds_dwordx4 v[26:27], off
	v_lshl_add_u64 v[26:27], v[28:29], 0, s[24:25]
	s_add_i32 m0, s53, 0x1a000
	s_add_i32 s27, s53, 0x8000
	v_lshl_add_u64 v[36:37], s[40:41], 0, v[148:149]
	global_load_lds_dwordx4 v[26:27], off
	s_add_i32 s72, s53, 0xa000
	v_lshl_add_u64 v[30:31], s[44:45], 0, v[150:151]
	v_lshl_add_u64 v[32:33], s[44:45], 0, v[146:147]
	s_add_i32 m0, s53, 0x1c000
	v_lshl_add_u64 v[26:27], v[30:31], 0, s[24:25]
	global_load_lds_dwordx4 v[26:27], off
	v_lshl_add_u64 v[26:27], v[32:33], 0, s[24:25]
	s_add_i32 m0, s53, 0x1e000
	s_andn2_b64 vcc, exec, s[38:39]
	global_load_lds_dwordx4 v[26:27], off
	s_waitcnt vmcnt(4)
	s_barrier
	s_cbranch_vccnz .LBB0_462
	s_waitcnt vmcnt(0)
	v_mov_b32_e32 v26, v15
	v_mov_b32_e32 v27, v16
	v_mov_b32_e32 v15, v17
	v_mov_b32_e32 v16, v11
	v_mov_b32_e32 v17, v12
	v_mov_b32_e32 v11, v13
	v_pk_add_f32 v[14:15], v[26:27], v[14:15]
	v_pk_add_f32 v[10:11], v[16:17], v[10:11]
	v_add_f32_e32 v14, v14, v15
	v_pk_add_f32 v[10:11], v[10:11], v[10:11] op_sel_hi:[0,1]
	v_add_f32_e32 v15, 0, v14
	v_add_f32_e32 v7, v6, v7
	v_add_f32_e32 v9, v8, v9
	v_mov_b32_e32 v6, v2
	v_mov_b32_e32 v8, v3
	v_mov_b32_e32 v10, v4
	v_mov_b32_e32 v14, v5
	v_pk_add_f32 v[2:3], v[6:7], v[8:9]
	v_pk_add_f32 v[4:5], v[10:11], v[14:15]
	s_nop 0
	v_pk_add_f32 v[2:3], v[2:3], v[4:5]
	s_nop 0
	v_add_f32_e32 v2, v2, v3
	v_fmamk_f32 v2, v2, 0x3a800000, v191
	v_mul_f32_e32 v3, 0x4b800000, v2
	v_cmp_gt_f32_e32 vcc, s96, v2
	s_nop 1
	v_cndmask_b32_e32 v2, v2, v3, vcc
	v_rsq_f32_e32 v2, v2
	s_nop 0
	v_mul_f32_e32 v3, 0x45800000, v2
	v_cndmask_b32_e32 v2, v2, v3, vcc
	v_lshl_add_u32 v3, v18, 2, 0
	v_add_u32_e32 v3, 0x20400, v3
	ds_write_b32 v3, v2

.LBB0_467:
	s_add_i32 s46, s42, 2
	s_add_u32 s47, s40, 0x80
	s_addc_u32 s43, s41, 0
	s_add_i32 s50, 0, 0x10000
	s_cmp_eq_u32 s75, s42
	s_cselect_b32 s43, s28, s43
	s_cselect_b32 s42, s29, s47
	v_add_u32_e32 v0, s50, v180
	s_cselect_b32 s49, s81, s45
	s_cselect_b32 s48, s80, s44
	s_add_i32 s47, 0, 0x14000
	ds_read_b128 v[130:133], v0
	ds_read_b128 v[134:137], v0 offset:1024
	ds_read_b128 v[138:141], v0 offset:2048
	ds_read_b128 v[142:145], v0 offset:3072
	v_add_u32_e32 v0, s47, v180
	ds_read_b128 v[158:161], v0
	ds_read_b128 v[162:165], v0 offset:1024
	ds_read_b128 v[166:169], v0 offset:2048
	ds_read_b128 v[170:173], v0 offset:3072
	v_lshl_add_u64 v[220:221], s[40:41], 0, v[152:153]
	s_mov_b32 m0, s27
	ds_read_b128 v[174:177], v181
	ds_read_b128 v[182:185], v181 offset:1024
	ds_read_b128 v[186:189], v181 offset:2048
	ds_read_b128 v[200:203], v181 offset:3072
	ds_read_b128 v[204:207], v181 offset:4096
	ds_read_b128 v[208:211], v181 offset:5120
	ds_read_b128 v[212:215], v181 offset:6144
	ds_read_b128 v[216:219], v181 offset:7168
	global_load_lds_dwordx4 v[220:221], off
	v_lshl_add_u64 v[220:221], s[40:41], 0, v[148:149]
	s_mov_b32 m0, s72
	s_nop 0
	global_load_lds_dwordx4 v[220:221], off
	v_lshl_add_u64 v[220:221], s[40:41], 0, v[154:155]
	s_add_i32 m0, s53, 0xc000
	s_nop 0
	global_load_lds_dwordx4 v[220:221], off
	v_lshl_add_u64 v[220:221], s[40:41], 0, v[156:157]
	s_add_i32 m0, s53, 0xe000
	s_nop 0
	global_load_lds_dwordx4 v[220:221], off
	s_waitcnt vmcnt(8)
	s_waitcnt lgkmcnt(0)
	s_barrier
	s_setprio 1
	s_waitcnt lgkmcnt(0)
	v_mfma_f32_16x16x32_bf16 v[126:129], v[130:133], v[174:177], v[126:129]
	v_mfma_f32_16x16x32_bf16 v[122:125], v[138:141], v[174:177], v[122:125]
	v_mfma_f32_16x16x32_bf16 v[110:113], v[130:133], v[186:189], v[110:113]
	v_mfma_f32_16x16x32_bf16 v[106:109], v[138:141], v[186:189], v[106:109]
	v_mfma_f32_16x16x32_bf16 v[94:97], v[130:133], v[204:207], v[94:97]
	v_mfma_f32_16x16x32_bf16 v[90:93], v[138:141], v[204:207], v[90:93]
	v_mfma_f32_16x16x32_bf16 v[78:81], v[130:133], v[212:215], v[78:81]
	v_mfma_f32_16x16x32_bf16 v[74:77], v[138:141], v[212:215], v[74:77]
	v_mfma_f32_16x16x32_bf16 v[126:129], v[134:137], v[182:185], v[126:129]
	v_mfma_f32_16x16x32_bf16 v[122:125], v[142:145], v[182:185], v[122:125]
	v_mfma_f32_16x16x32_bf16 v[110:113], v[134:137], v[200:203], v[110:113]
	v_mfma_f32_16x16x32_bf16 v[106:109], v[142:145], v[200:203], v[106:109]
	v_mfma_f32_16x16x32_bf16 v[94:97], v[134:137], v[208:211], v[94:97]
	v_mfma_f32_16x16x32_bf16 v[90:93], v[142:145], v[208:211], v[90:93]
	v_mfma_f32_16x16x32_bf16 v[78:81], v[134:137], v[216:219], v[78:81]
	v_mfma_f32_16x16x32_bf16 v[74:77], v[142:145], v[216:219], v[74:77]
	s_setprio 0
	s_setprio 1
	v_mfma_f32_16x16x32_bf16 v[118:121], v[158:161], v[174:177], v[118:121]
	v_mfma_f32_16x16x32_bf16 v[114:117], v[166:169], v[174:177], v[114:117]
	v_mfma_f32_16x16x32_bf16 v[102:105], v[158:161], v[186:189], v[102:105]
	v_mfma_f32_16x16x32_bf16 v[98:101], v[166:169], v[186:189], v[98:101]
	v_mfma_f32_16x16x32_bf16 v[86:89], v[158:161], v[204:207], v[86:89]
	v_mfma_f32_16x16x32_bf16 v[82:85], v[166:169], v[204:207], v[82:85]
	v_mfma_f32_16x16x32_bf16 v[70:73], v[158:161], v[212:215], v[70:73]
	v_mfma_f32_16x16x32_bf16 v[66:69], v[166:169], v[212:215], v[66:69]
	v_mfma_f32_16x16x32_bf16 v[118:121], v[162:165], v[182:185], v[118:121]
	v_mfma_f32_16x16x32_bf16 v[114:117], v[170:173], v[182:185], v[114:117]
	v_mfma_f32_16x16x32_bf16 v[102:105], v[162:165], v[200:203], v[102:105]
	v_mfma_f32_16x16x32_bf16 v[98:101], v[170:173], v[200:203], v[98:101]
	v_mfma_f32_16x16x32_bf16 v[86:89], v[162:165], v[208:211], v[86:89]
	v_mfma_f32_16x16x32_bf16 v[82:85], v[170:173], v[208:211], v[82:85]
	v_mfma_f32_16x16x32_bf16 v[70:73], v[162:165], v[216:219], v[70:73]
	v_mfma_f32_16x16x32_bf16 v[66:69], v[170:173], v[216:219], v[66:69]
	s_setprio 0
	s_barrier
	s_add_i32 s50, s50, s31
	v_lshl_add_u64 v[220:221], s[48:49], 0, v[150:151]
	s_mov_b32 m0, s50
	ds_read_b128 v[174:177], v181 offset:16384
	ds_read_b128 v[182:185], v181 offset:17408
	ds_read_b128 v[186:189], v181 offset:18432
	ds_read_b128 v[200:203], v181 offset:19456
	ds_read_b128 v[204:207], v181 offset:20480
	ds_read_b128 v[208:211], v181 offset:21504
	ds_read_b128 v[212:215], v181 offset:22528
	ds_read_b128 v[216:219], v181 offset:23552
	global_load_lds_dwordx4 v[220:221], off
	s_add_i32 m0, s50, 0x2000
	v_lshl_add_u64 v[222:223], s[48:49], 0, v[146:147]
	s_add_u32 s48, s48, s56
	s_addc_u32 s49, s49, s57
	s_add_i32 s47, s47, s31
	global_load_lds_dwordx4 v[222:223], off
	v_lshl_add_u64 v[224:225], s[48:49], 0, v[150:151]
	s_mov_b32 m0, s47
	v_lshl_add_u64 v[226:227], s[48:49], 0, v[146:147]
	global_load_lds_dwordx4 v[224:225], off
	s_add_i32 m0, s47, 0x2000
	v_lshl_add_u64 v[228:229], s[42:43], 0, v[152:153]
	global_load_lds_dwordx4 v[226:227], off
	v_lshl_add_u64 v[230:231], s[42:43], 0, v[148:149]
	s_waitcnt vmcnt(6)
	s_waitcnt lgkmcnt(0)
	s_barrier
	s_setprio 1
	s_waitcnt lgkmcnt(0)
	v_mfma_f32_16x16x32_bf16 v[62:65], v[130:133], v[174:177], v[62:65]
	v_mfma_f32_16x16x32_bf16 v[58:61], v[138:141], v[174:177], v[58:61]
	v_mfma_f32_16x16x32_bf16 v[46:49], v[130:133], v[186:189], v[46:49]
	v_mfma_f32_16x16x32_bf16 v[42:45], v[138:141], v[186:189], v[42:45]
	v_mfma_f32_16x16x32_bf16 v[30:33], v[130:133], v[204:207], v[30:33]
	v_mfma_f32_16x16x32_bf16 v[26:29], v[138:141], v[204:207], v[26:29]
	v_mfma_f32_16x16x32_bf16 v[14:17], v[130:133], v[212:215], v[14:17]
	v_mfma_f32_16x16x32_bf16 v[10:13], v[138:141], v[212:215], v[10:13]
	v_mfma_f32_16x16x32_bf16 v[62:65], v[134:137], v[182:185], v[62:65]
	v_mfma_f32_16x16x32_bf16 v[58:61], v[142:145], v[182:185], v[58:61]
	v_mfma_f32_16x16x32_bf16 v[46:49], v[134:137], v[200:203], v[46:49]
	v_mfma_f32_16x16x32_bf16 v[42:45], v[142:145], v[200:203], v[42:45]
	v_mfma_f32_16x16x32_bf16 v[30:33], v[134:137], v[208:211], v[30:33]
	v_mfma_f32_16x16x32_bf16 v[26:29], v[142:145], v[208:211], v[26:29]
	v_mfma_f32_16x16x32_bf16 v[14:17], v[134:137], v[216:219], v[14:17]
	v_mfma_f32_16x16x32_bf16 v[10:13], v[142:145], v[216:219], v[10:13]
	s_setprio 0
	s_setprio 1
	v_mfma_f32_16x16x32_bf16 v[54:57], v[158:161], v[174:177], v[54:57]
	v_mfma_f32_16x16x32_bf16 v[50:53], v[166:169], v[174:177], v[50:53]
	v_mfma_f32_16x16x32_bf16 v[38:41], v[158:161], v[186:189], v[38:41]
	v_mfma_f32_16x16x32_bf16 v[34:37], v[166:169], v[186:189], v[34:37]
	v_mfma_f32_16x16x32_bf16 v[22:25], v[158:161], v[204:207], v[22:25]
	v_mfma_f32_16x16x32_bf16 v[18:21], v[166:169], v[204:207], v[18:21]
	v_mfma_f32_16x16x32_bf16 v[6:9], v[158:161], v[212:215], v[6:9]
	v_mfma_f32_16x16x32_bf16 v[2:5], v[166:169], v[212:215], v[2:5]
	v_mfma_f32_16x16x32_bf16 v[54:57], v[162:165], v[182:185], v[54:57]
	v_mfma_f32_16x16x32_bf16 v[50:53], v[170:173], v[182:185], v[50:53]
	v_mfma_f32_16x16x32_bf16 v[38:41], v[162:165], v[200:203], v[38:41]
	v_mfma_f32_16x16x32_bf16 v[34:37], v[170:173], v[200:203], v[34:37]
	v_mfma_f32_16x16x32_bf16 v[22:25], v[162:165], v[208:211], v[22:25]
	v_mfma_f32_16x16x32_bf16 v[18:21], v[170:173], v[208:211], v[18:21]
	v_mfma_f32_16x16x32_bf16 v[6:9], v[162:165], v[216:219], v[6:9]
	v_mfma_f32_16x16x32_bf16 v[2:5], v[170:173], v[216:219], v[2:5]
	s_setprio 0
	s_barrier
	s_add_i32 s47, 0, 0x18000
	v_add_u32_e32 v0, s47, v180
	s_add_i32 s48, 0, 0x1c000
	ds_read_b128 v[130:133], v0
	ds_read_b128 v[134:137], v0 offset:1024
	ds_read_b128 v[138:141], v0 offset:2048
	ds_read_b128 v[142:145], v0 offset:3072
	v_add_u32_e32 v0, s48, v180
	ds_read_b128 v[158:161], v0
	ds_read_b128 v[162:165], v0 offset:1024
	ds_read_b128 v[166:169], v0 offset:2048
	ds_read_b128 v[170:173], v0 offset:3072
	s_add_u32 s42, s42, s54
	s_addc_u32 s43, s43, s55
	s_mov_b32 m0, s53
	v_lshl_add_u64 v[232:233], s[42:43], 0, v[152:153]
	ds_read_b128 v[174:177], v181 offset:32768
	ds_read_b128 v[182:185], v181 offset:33792
	ds_read_b128 v[186:189], v181 offset:34816
	ds_read_b128 v[200:203], v181 offset:35840
	ds_read_b128 v[204:207], v181 offset:36864
	ds_read_b128 v[208:211], v181 offset:37888
	ds_read_b128 v[212:215], v181 offset:38912
	ds_read_b128 v[216:219], v181 offset:39936
	global_load_lds_dwordx4 v[228:229], off
	s_mov_b32 m0, s4
	s_nop 0
	global_load_lds_dwordx4 v[230:231], off
	s_mov_b32 m0, s82
	s_nop 0
	global_load_lds_dwordx4 v[232:233], off
	v_lshl_add_u64 v[232:233], s[42:43], 0, v[148:149]
	s_mov_b32 m0, s83
	s_nop 0
	global_load_lds_dwordx4 v[232:233], off
	s_waitcnt vmcnt(8)
	s_waitcnt lgkmcnt(0)
	s_barrier
	s_setprio 1
	s_waitcnt lgkmcnt(0)
	v_mfma_f32_16x16x32_bf16 v[126:129], v[130:133], v[174:177], v[126:129]
	v_mfma_f32_16x16x32_bf16 v[122:125], v[138:141], v[174:177], v[122:125]
	v_mfma_f32_16x16x32_bf16 v[110:113], v[130:133], v[186:189], v[110:113]
	v_mfma_f32_16x16x32_bf16 v[106:109], v[138:141], v[186:189], v[106:109]
	v_mfma_f32_16x16x32_bf16 v[94:97], v[130:133], v[204:207], v[94:97]
	v_mfma_f32_16x16x32_bf16 v[90:93], v[138:141], v[204:207], v[90:93]
	v_mfma_f32_16x16x32_bf16 v[78:81], v[130:133], v[212:215], v[78:81]
	v_mfma_f32_16x16x32_bf16 v[74:77], v[138:141], v[212:215], v[74:77]
	v_mfma_f32_16x16x32_bf16 v[126:129], v[134:137], v[182:185], v[126:129]
	v_mfma_f32_16x16x32_bf16 v[122:125], v[142:145], v[182:185], v[122:125]
	v_mfma_f32_16x16x32_bf16 v[110:113], v[134:137], v[200:203], v[110:113]
	v_mfma_f32_16x16x32_bf16 v[106:109], v[142:145], v[200:203], v[106:109]
	v_mfma_f32_16x16x32_bf16 v[94:97], v[134:137], v[208:211], v[94:97]
	v_mfma_f32_16x16x32_bf16 v[90:93], v[142:145], v[208:211], v[90:93]
	v_mfma_f32_16x16x32_bf16 v[78:81], v[134:137], v[216:219], v[78:81]
	v_mfma_f32_16x16x32_bf16 v[74:77], v[142:145], v[216:219], v[74:77]
	s_setprio 0
	s_setprio 1
	v_mfma_f32_16x16x32_bf16 v[118:121], v[158:161], v[174:177], v[118:121]
	v_mfma_f32_16x16x32_bf16 v[114:117], v[166:169], v[174:177], v[114:117]
	v_mfma_f32_16x16x32_bf16 v[102:105], v[158:161], v[186:189], v[102:105]
	v_mfma_f32_16x16x32_bf16 v[98:101], v[166:169], v[186:189], v[98:101]
	v_mfma_f32_16x16x32_bf16 v[86:89], v[158:161], v[204:207], v[86:89]
	v_mfma_f32_16x16x32_bf16 v[82:85], v[166:169], v[204:207], v[82:85]
	v_mfma_f32_16x16x32_bf16 v[70:73], v[158:161], v[212:215], v[70:73]
	v_mfma_f32_16x16x32_bf16 v[66:69], v[166:169], v[212:215], v[66:69]
	v_mfma_f32_16x16x32_bf16 v[118:121], v[162:165], v[182:185], v[118:121]
	v_mfma_f32_16x16x32_bf16 v[114:117], v[170:173], v[182:185], v[114:117]
	v_mfma_f32_16x16x32_bf16 v[102:105], v[162:165], v[200:203], v[102:105]
	v_mfma_f32_16x16x32_bf16 v[98:101], v[170:173], v[200:203], v[98:101]
	v_mfma_f32_16x16x32_bf16 v[86:89], v[162:165], v[208:211], v[86:89]
	v_mfma_f32_16x16x32_bf16 v[82:85], v[170:173], v[208:211], v[82:85]
	v_mfma_f32_16x16x32_bf16 v[70:73], v[162:165], v[216:219], v[70:73]
	v_mfma_f32_16x16x32_bf16 v[66:69], v[170:173], v[216:219], v[66:69]
	s_setprio 0
	s_barrier
	s_add_i32 s42, s47, s31
	v_lshl_add_u64 v[220:221], v[220:221], 0, s[24:25]
	s_mov_b32 m0, s42
	ds_read_b128 v[174:177], v181 offset:49152
	ds_read_b128 v[182:185], v181 offset:50176
	ds_read_b128 v[186:189], v181 offset:51200
	ds_read_b128 v[200:203], v181 offset:52224
	ds_read_b128 v[204:207], v181 offset:53248
	ds_read_b128 v[208:211], v181 offset:54272
	ds_read_b128 v[212:215], v181 offset:55296
	ds_read_b128 v[216:219], v181 offset:56320
	global_load_lds_dwordx4 v[220:221], off
	v_lshl_add_u64 v[220:221], v[222:223], 0, s[24:25]
	s_add_i32 m0, s42, 0x2000
	s_add_i32 s42, s48, s31
	global_load_lds_dwordx4 v[220:221], off
	v_lshl_add_u64 v[220:221], v[224:225], 0, s[24:25]
	s_mov_b32 m0, s42
	s_nop 0
	global_load_lds_dwordx4 v[220:221], off
	v_lshl_add_u64 v[220:221], v[226:227], 0, s[24:25]
	s_add_i32 m0, s42, 0x2000
	s_nop 0
	global_load_lds_dwordx4 v[220:221], off
	s_waitcnt vmcnt(6)
	s_waitcnt lgkmcnt(0)
	s_barrier
	s_setprio 1
	s_waitcnt lgkmcnt(0)
	v_mfma_f32_16x16x32_bf16 v[62:65], v[130:133], v[174:177], v[62:65]
	v_mfma_f32_16x16x32_bf16 v[58:61], v[138:141], v[174:177], v[58:61]
	v_mfma_f32_16x16x32_bf16 v[46:49], v[130:133], v[186:189], v[46:49]
	v_mfma_f32_16x16x32_bf16 v[42:45], v[138:141], v[186:189], v[42:45]
	v_mfma_f32_16x16x32_bf16 v[30:33], v[130:133], v[204:207], v[30:33]
	v_mfma_f32_16x16x32_bf16 v[26:29], v[138:141], v[204:207], v[26:29]
	v_mfma_f32_16x16x32_bf16 v[14:17], v[130:133], v[212:215], v[14:17]
	v_mfma_f32_16x16x32_bf16 v[10:13], v[138:141], v[212:215], v[10:13]
	v_mfma_f32_16x16x32_bf16 v[62:65], v[134:137], v[182:185], v[62:65]
	v_mfma_f32_16x16x32_bf16 v[58:61], v[142:145], v[182:185], v[58:61]
	v_mfma_f32_16x16x32_bf16 v[46:49], v[134:137], v[200:203], v[46:49]
	v_mfma_f32_16x16x32_bf16 v[42:45], v[142:145], v[200:203], v[42:45]
	v_mfma_f32_16x16x32_bf16 v[30:33], v[134:137], v[208:211], v[30:33]
	v_mfma_f32_16x16x32_bf16 v[26:29], v[142:145], v[208:211], v[26:29]
	v_mfma_f32_16x16x32_bf16 v[14:17], v[134:137], v[216:219], v[14:17]
	v_mfma_f32_16x16x32_bf16 v[10:13], v[142:145], v[216:219], v[10:13]
	s_setprio 0
	s_setprio 1
	v_mfma_f32_16x16x32_bf16 v[54:57], v[158:161], v[174:177], v[54:57]
	v_mfma_f32_16x16x32_bf16 v[50:53], v[166:169], v[174:177], v[50:53]
	v_mfma_f32_16x16x32_bf16 v[38:41], v[158:161], v[186:189], v[38:41]
	v_mfma_f32_16x16x32_bf16 v[34:37], v[166:169], v[186:189], v[34:37]
	v_mfma_f32_16x16x32_bf16 v[22:25], v[158:161], v[204:207], v[22:25]
	v_mfma_f32_16x16x32_bf16 v[18:21], v[166:169], v[204:207], v[18:21]
	v_mfma_f32_16x16x32_bf16 v[6:9], v[158:161], v[212:215], v[6:9]
	v_mfma_f32_16x16x32_bf16 v[2:5], v[166:169], v[212:215], v[2:5]
	v_mfma_f32_16x16x32_bf16 v[54:57], v[162:165], v[182:185], v[54:57]
	v_mfma_f32_16x16x32_bf16 v[50:53], v[170:173], v[182:185], v[50:53]
	v_mfma_f32_16x16x32_bf16 v[38:41], v[162:165], v[200:203], v[38:41]
	v_mfma_f32_16x16x32_bf16 v[34:37], v[170:173], v[200:203], v[34:37]
	v_mfma_f32_16x16x32_bf16 v[22:25], v[162:165], v[208:211], v[22:25]
	v_mfma_f32_16x16x32_bf16 v[18:21], v[170:173], v[208:211], v[18:21]
	v_mfma_f32_16x16x32_bf16 v[6:9], v[162:165], v[216:219], v[6:9]
	v_mfma_f32_16x16x32_bf16 v[2:5], v[170:173], v[216:219], v[2:5]
	s_setprio 0
	s_barrier
	s_add_u32 s40, s40, 0x100
	s_addc_u32 s41, s41, 0
	s_add_u32 s44, s44, 0x100
	s_addc_u32 s45, s45, 0
	s_cmp_ge_i32 s46, s74
	s_mov_b32 s42, s46
	s_cbranch_scc0 .LBB0_467
